# SSD scan pass: per-chunk 128-wide prefix/suffix scans via DPP (row_shr/row_bcast/readlane) instead of 14 ds_bpermute round trips
# speedup vs baseline: 1.0221x; 1.0107x over previous
; __device__ __forceinline__ f32x2 scan128(float s0, float s1, int lane, int dir) {
;     if (dir == 0) {
; #pragma unroll
;         for (int o = 1; o < 64; o <<= 1) { const float t0 = __shfl_up(s0, o), t1 = __shfl_up(s1, o); s0 += lane >= o ? t0 : 0.f; s1 += lane >= o ? t1 : 0.f; }
;         s1 += __shfl(s0, 63);
;     } else {
; #pragma unroll
;         for (int o = 1; o < 64; o <<= 1) { const float t0 = __shfl_down(s0, o), t1 = __shfl_down(s1, o); s0 += lane + o < 64 ? t0 : 0.f; s1 += lane + o < 64 ? t1 : 0.f; }
;         s0 += __shfl(s1, 0);
;     }
;     return (f32x2){s0, s1};
; }
; __device__ __forceinline__ void ssd_scan_item(CParams& p, int j2, int b, int dir, int h, int pq, bf16_t* smem) {
;     ...
;         lds_sync();
;         *(u32x4*)(sX + (tid >> 4) * SST + (tid & 15) * 8) = S.xq;
; #pragma unroll
;         for (int nt = 0; nt < 2; ++nt) st4bf(sH + l16 * SST + wave * 32 + nt * 16 + quad * 4, st[nt][0], st[nt][1], st[nt][2], st[nt][3]);
;         if (wave < 2) {
;             const f32x2 sc2 = scan128(S.dt0 * a, S.dt1 * a, lane, dir);
;             const float total = dir == 0 ? __shfl(sc2.y, 63) : __shfl(sc2.x, 0);
;             if (wave == 0) { seacs[lane] = __expf(sc2.x); sw[lane] = S.dt0 * __expf(total - sc2.x); if (lane == 0) sdec[0] = __expf(total); }
;             else { seacs[64 + lane] = __expf(sc2.y); sw[64 + lane] = S.dt1 * __expf(total - sc2.y); }
;         }
.LBB0_463:
	s_mov_b64 s[22:23], -1
	s_cmpk_gt_u32 s77, 0x41
	s_waitcnt vmcnt(23)
	v_readfirstlane_b32 s21, v0
	v_readfirstlane_b32 s24, v0
	s_cbranch_scc1 .LBB0_462
	v_ashrrev_i32_e32 v100, 5, v100
	v_ashrrev_i32_e32 v101, 31, v100
	v_lshlrev_b64 v[100:101], 10, v[100:101]
	v_lshl_add_u64 v[104:105], v[154:155], 0, v[100:101]
	global_load_dwordx4 v[128:131], v[104:105], off
	global_load_dwordx4 v[120:123], v[104:105], off offset:1024
	global_load_dwordx4 v[112:115], v[104:105], off offset:2048
	global_load_dwordx4 v[100:103], v[104:105], off offset:3072
	v_add_co_u32_e32 v104, vcc, 0x84000, v104
	v_add_u32_e32 v176, 0x1000, v169
	s_nop 0
	v_addc_co_u32_e32 v105, vcc, 0, v105, vcc
	global_load_dwordx4 v[132:135], v[104:105], off
	global_load_dwordx4 v[124:127], v[104:105], off offset:1024
	global_load_dwordx4 v[116:119], v[104:105], off offset:2048
	s_nop 0
	global_load_dwordx4 v[104:107], v[104:105], off offset:3072
	s_barrier
	ds_write_b128 v164, v[88:91]
	v_cvt_pk_bf16_f32 v88, v136, v137
	v_cvt_pk_bf16_f32 v89, v138, v139
	v_cvt_pk_bf16_f32 v90, v140, v141
	v_cvt_pk_bf16_f32 v91, v142, v143
	ds_write2_b64 v176, v[88:89], v[90:91] offset0:32 offset1:36
	v_cndmask_b32_e64 v88, 0, 1, s[14:15]
	v_cmp_ne_u32_e64 s[70:71], 1, v88
	s_and_saveexec_b64 s[20:21], s[44:45]
	s_cbranch_execz .LBB0_478
	v_mul_f32_e64 v90, v161, -v163
	v_mul_f32_e64 v89, v162, -v163
	s_and_b64 vcc, exec, s[70:71]
	v_mov_b32_e32 v91, v90
	v_mov_b32_e32 v178, v89
	s_cbranch_vccz .Lsc0_bwd
	v_add_f32_dpp v91, v90, v91 row_shr:1 row_mask:0xf bank_mask:0xf bound_ctrl:0
	v_add_f32_dpp v178, v89, v178 row_shr:1 row_mask:0xf bank_mask:0xf bound_ctrl:0
	v_add_f32_dpp v91, v90, v91 row_shr:2 row_mask:0xf bank_mask:0xf bound_ctrl:0
	v_add_f32_dpp v178, v89, v178 row_shr:2 row_mask:0xf bank_mask:0xf bound_ctrl:0
	v_add_f32_dpp v91, v90, v91 row_shr:3 row_mask:0xf bank_mask:0xf bound_ctrl:0
	v_add_f32_dpp v178, v89, v178 row_shr:3 row_mask:0xf bank_mask:0xf bound_ctrl:0
	s_nop 1
	v_add_f32_dpp v91, v91, v91 row_shr:4 row_mask:0xf bank_mask:0xe
	v_add_f32_dpp v178, v178, v178 row_shr:4 row_mask:0xf bank_mask:0xe
	s_nop 1
	v_add_f32_dpp v91, v91, v91 row_shr:8 row_mask:0xf bank_mask:0xc
	v_add_f32_dpp v178, v178, v178 row_shr:8 row_mask:0xf bank_mask:0xc
	s_nop 1
	v_add_f32_dpp v91, v91, v91 row_bcast:15 row_mask:0xa bank_mask:0xf
	v_add_f32_dpp v178, v178, v178 row_bcast:15 row_mask:0xa bank_mask:0xf
	s_nop 1
	v_add_f32_dpp v91, v91, v91 row_bcast:31 row_mask:0xc bank_mask:0xf
	v_add_f32_dpp v178, v178, v178 row_bcast:31 row_mask:0xc bank_mask:0xf
	s_nop 1
	v_readlane_b32 s22, v91, 63
	s_nop 3
	v_add_f32_e32 v178, s22, v178
	s_nop 1
	v_readlane_b32 s22, v178, 63
	s_nop 3
	v_mov_b32_e32 v88, s22
	s_branch .Lsc0_join
.Lsc0_bwd:
	v_add_f32_dpp v91, v90, v91 row_shl:1 row_mask:0xf bank_mask:0xf bound_ctrl:0
	v_add_f32_dpp v178, v89, v178 row_shl:1 row_mask:0xf bank_mask:0xf bound_ctrl:0
	v_add_f32_dpp v91, v90, v91 row_shl:2 row_mask:0xf bank_mask:0xf bound_ctrl:0
	v_add_f32_dpp v178, v89, v178 row_shl:2 row_mask:0xf bank_mask:0xf bound_ctrl:0
	v_add_f32_dpp v91, v90, v91 row_shl:3 row_mask:0xf bank_mask:0xf bound_ctrl:0
	v_add_f32_dpp v178, v89, v178 row_shl:3 row_mask:0xf bank_mask:0xf bound_ctrl:0
	s_nop 1
	v_add_f32_dpp v91, v91, v91 row_shl:4 row_mask:0xf bank_mask:0x7
	v_add_f32_dpp v178, v178, v178 row_shl:4 row_mask:0xf bank_mask:0x7
	s_nop 1
	v_add_f32_dpp v91, v91, v91 row_shl:8 row_mask:0xf bank_mask:0x3
	v_add_f32_dpp v178, v178, v178 row_shl:8 row_mask:0xf bank_mask:0x3
	s_nop 1
	v_readlane_b32 s22, v91, 48
	v_readlane_b32 s23, v178, 48
	s_nop 3
	v_mov_b32_e32 v177, s22
	v_mov_b32_e32 v179, s23
	s_nop 1
	v_add_f32_dpp v91, v177, v91 quad_perm:[0,1,2,3] row_mask:0x4 bank_mask:0xf
	v_add_f32_dpp v178, v179, v178 quad_perm:[0,1,2,3] row_mask:0x4 bank_mask:0xf
	s_nop 1
	v_readlane_b32 s22, v91, 32
	v_readlane_b32 s23, v178, 32
	s_nop 3
	v_mov_b32_e32 v177, s22
	v_mov_b32_e32 v179, s23
	s_nop 1
	v_add_f32_dpp v91, v177, v91 quad_perm:[0,1,2,3] row_mask:0x2 bank_mask:0xf
	v_add_f32_dpp v178, v179, v178 quad_perm:[0,1,2,3] row_mask:0x2 bank_mask:0xf
	s_nop 1
	v_readlane_b32 s22, v91, 16
	v_readlane_b32 s23, v178, 16
	s_nop 3
	v_mov_b32_e32 v177, s22
	v_mov_b32_e32 v179, s23
	s_nop 1
	v_add_f32_dpp v91, v177, v91 quad_perm:[0,1,2,3] row_mask:0x1 bank_mask:0xf
	v_add_f32_dpp v178, v179, v178 quad_perm:[0,1,2,3] row_mask:0x1 bank_mask:0xf
	s_nop 1
	v_readlane_b32 s22, v178, 0
	s_nop 3
	v_add_f32_e32 v91, s22, v91
	s_nop 1
	v_readlane_b32 s22, v91, 0
	s_nop 3
	v_mov_b32_e32 v88, s22
.Lsc0_join:
	s_and_saveexec_b64 s[22:23], s[68:69]
	s_xor_b64 s[22:23], exec, s[22:23]
	s_cbranch_execz .Lsc0_w0
	v_sub_f32_e32 v88, v88, v178
	v_mul_f32_e32 v88, 0x3fb8aa3b, v88
	v_mul_f32_e32 v89, 0x3fb8aa3b, v178
	v_exp_f32_e32 v88, v88
	v_exp_f32_e32 v89, v89
	s_nop 0
	v_mul_f32_e32 v88, v162, v88
	ds_write2st64_b32 v174, v89, v88 offset0:35 offset1:37
.Lsc0_w0:
	s_andn2_saveexec_b64 s[22:23], s[22:23]
	s_cbranch_execz .LBB0_478
	v_sub_f32_e32 v90, v88, v91
	v_mul_f32_e32 v90, 0x3fb8aa3b, v90
	v_mul_f32_e32 v89, 0x3fb8aa3b, v91
	v_exp_f32_e32 v90, v90
	v_exp_f32_e32 v89, v89
	s_nop 0
	v_mul_f32_e32 v90, v161, v90
	ds_write2st64_b32 v174, v89, v90 offset0:34 offset1:36
	s_and_b64 exec, exec, s[58:59]
	s_cbranch_execz .LBB0_478
	v_mul_f32_e32 v88, 0x3fb8aa3b, v88
	v_exp_f32_e32 v88, v88
	ds_write_b32 v165, v88 offset:9728

; __device__ __forceinline__ unsigned pack2(float a, float b) { const f32v2_t v = {a, b}; return __builtin_bit_cast(unsigned, __builtin_convertvector(v, bf16v2_t)); }
; __device__ __forceinline__ f32x4 mfma16(bf16x8 a, bf16x8 b, f32x4 c) { return __builtin_amdgcn_mfma_f32_16x16x32_bf16(a, b, c, 0, 0, 0); }
; __device__ __forceinline__ void ssd_scan_item(CParams& p, int j2, int b, int dir, int h, int pq, bf16_t* smem) {
;     ...
;         lds_sync();
;         *(u32x4*)(sX + (tid >> 4) * SST + (tid & 15) * 8) = S.xq;
; #pragma unroll
;         for (int nt = 0; nt < 2; ++nt) st4bf(sH + l16 * SST + wave * 32 + nt * 16 + quad * 4, st[nt][0], st[nt][1], st[nt][2], st[nt][3]);
;         if (wave < 2) {
;             const f32x2 sc2 = scan128(S.dt0 * a, S.dt1 * a, lane, dir);
;     ...
;         {
;             const float dec = sdec[0];
;             st[0] *= dec; st[1] *= dec;
; #pragma unroll
;             for (int ks = 0; ks < 4; ++ks) {
;                 const f32x4 w0 = *(const f32x4*)(sw + ks * 32 + quad * 8), w1 = *(const f32x4*)(sw + ks * 32 + quad * 8 + 4);
;                 const u32x4 raw = *(const u32x4*)(sX + l16 * SST + ks * 32 + quad * 8);
;                 u32x4 xs;
;                 xs.x = pack2(__uint_as_float(raw.x << 16) * w0[0], __uint_as_float(raw.x & 0xffff0000u) * w0[1]);
;                 xs.y = pack2(__uint_as_float(raw.y << 16) * w0[2], __uint_as_float(raw.y & 0xffff0000u) * w0[3]);
;                 xs.z = pack2(__uint_as_float(raw.z << 16) * w1[0], __uint_as_float(raw.z & 0xffff0000u) * w1[1]);
;                 xs.w = pack2(__uint_as_float(raw.w << 16) * w1[2], __uint_as_float(raw.w & 0xffff0000u) * w1[3]);
;                 const bf16x8 xbf = __builtin_bit_cast(bf16x8, xs);
; #pragma unroll
;                 for (int nt = 0; nt < 2; ++nt) st[nt] = mfma16(__builtin_bit_cast(bf16x8, S.bt[nt][ks]), xbf, st[nt]);
;             }
;         }
;         __builtin_amdgcn_sched_barrier(0);
;         load_bt(S, row2);
.LBB0_482:
	ds_read_b32 v178, v165 offset:9728
	s_waitcnt lgkmcnt(0)
	v_pk_mul_f32 v[138:139], v[138:139], v[178:179] op_sel_hi:[1,0]
	v_pk_mul_f32 v[136:137], v[136:137], v[178:179] op_sel_hi:[1,0]
	v_pk_mul_f32 v[142:143], v[142:143], v[178:179] op_sel_hi:[1,0]
	v_pk_mul_f32 v[140:141], v[140:141], v[178:179] op_sel_hi:[1,0]
	ds_read_b128 v[178:181], v172 offset:9216
	ds_read_b128 v[182:185], v172 offset:9232
	ds_read_b128 v[186:189], v170
	s_waitcnt lgkmcnt(0)
	v_lshlrev_b32_e32 v190, 16, v186
	v_and_b32_e32 v191, 0xffff0000, v186
	v_lshlrev_b32_e32 v186, 16, v187
	v_and_b32_e32 v187, 0xffff0000, v187
	v_pk_mul_f32 v[178:179], v[178:179], v[190:191]
	v_pk_mul_f32 v[180:181], v[180:181], v[186:187]
	v_cvt_pk_bf16_f32 v178, v178, v179
	v_cvt_pk_bf16_f32 v179, v180, v181
	v_lshlrev_b32_e32 v180, 16, v188
	v_and_b32_e32 v181, 0xffff0000, v188
	v_pk_mul_f32 v[180:181], v[182:183], v[180:181]
	v_lshlrev_b32_e32 v182, 16, v189
	v_and_b32_e32 v183, 0xffff0000, v189
	v_pk_mul_f32 v[182:183], v[184:185], v[182:183]
	v_cvt_pk_bf16_f32 v180, v180, v181
	v_cvt_pk_bf16_f32 v181, v182, v183
	s_waitcnt vmcnt(39)
	s_nop 0
	v_mfma_f32_16x16x32_bf16 v[92:95], v[92:95], v[178:181], v[136:139]
	s_waitcnt vmcnt(35)
	v_mfma_f32_16x16x32_bf16 v[96:99], v[96:99], v[178:181], v[140:143]
	s_nop 0
	ds_read_b128 v[136:139], v172 offset:9344
	s_nop 0
	ds_read_b128 v[140:143], v172 offset:9360
	ds_read_b128 v[178:181], v170 offset:64
	s_waitcnt lgkmcnt(0)
	v_lshlrev_b32_e32 v182, 16, v178
	v_and_b32_e32 v183, 0xffff0000, v178
	v_lshlrev_b32_e32 v178, 16, v179
	v_and_b32_e32 v179, 0xffff0000, v179
	v_pk_mul_f32 v[136:137], v[136:137], v[182:183]
	v_pk_mul_f32 v[138:139], v[138:139], v[178:179]
	v_cvt_pk_bf16_f32 v136, v136, v137
	v_cvt_pk_bf16_f32 v137, v138, v139
	v_lshlrev_b32_e32 v138, 16, v180
	v_and_b32_e32 v139, 0xffff0000, v180
	v_pk_mul_f32 v[138:139], v[140:141], v[138:139]
	v_lshlrev_b32_e32 v140, 16, v181
	v_and_b32_e32 v141, 0xffff0000, v181
	v_pk_mul_f32 v[140:141], v[142:143], v[140:141]
	v_cvt_pk_bf16_f32 v138, v138, v139
	v_cvt_pk_bf16_f32 v139, v140, v141
	s_nop 1
	v_mfma_f32_16x16x32_bf16 v[80:83], v[80:83], v[136:139], v[92:95]
	s_waitcnt vmcnt(34)
	v_mfma_f32_16x16x32_bf16 v[84:87], v[84:87], v[136:139], v[96:99]
	s_nop 0
	ds_read_b128 v[92:95], v172 offset:9472
	s_nop 0
	ds_read_b128 v[96:99], v172 offset:9488
	ds_read_b128 v[136:139], v170 offset:128
	s_waitcnt lgkmcnt(0)
	v_lshlrev_b32_e32 v140, 16, v136
	v_and_b32_e32 v141, 0xffff0000, v136
	v_lshlrev_b32_e32 v136, 16, v137
	v_and_b32_e32 v137, 0xffff0000, v137
	v_pk_mul_f32 v[92:93], v[92:93], v[140:141]
	v_pk_mul_f32 v[94:95], v[94:95], v[136:137]
	v_cvt_pk_bf16_f32 v92, v92, v93
	v_cvt_pk_bf16_f32 v93, v94, v95
	v_lshlrev_b32_e32 v94, 16, v138
	v_and_b32_e32 v95, 0xffff0000, v138
	v_pk_mul_f32 v[94:95], v[96:97], v[94:95]
	v_lshlrev_b32_e32 v96, 16, v139
	v_and_b32_e32 v97, 0xffff0000, v139
	v_pk_mul_f32 v[96:97], v[98:99], v[96:97]
	v_cvt_pk_bf16_f32 v94, v94, v95
	v_cvt_pk_bf16_f32 v95, v96, v97
	s_nop 1
	v_mfma_f32_16x16x32_bf16 v[72:75], v[72:75], v[92:95], v[80:83]
	s_waitcnt vmcnt(33)
	v_mfma_f32_16x16x32_bf16 v[76:79], v[76:79], v[92:95], v[84:87]
	s_nop 0
	ds_read_b128 v[80:83], v172 offset:9600
	s_nop 0
	ds_read_b128 v[84:87], v172 offset:9616
	ds_read_b128 v[92:95], v170 offset:192
	s_waitcnt lgkmcnt(0)
	v_lshlrev_b32_e32 v96, 16, v92
	v_and_b32_e32 v97, 0xffff0000, v92
	v_lshlrev_b32_e32 v92, 16, v93
	v_and_b32_e32 v93, 0xffff0000, v93
	v_pk_mul_f32 v[80:81], v[80:81], v[96:97]
	v_pk_mul_f32 v[82:83], v[82:83], v[92:93]
	v_cvt_pk_bf16_f32 v80, v80, v81
	v_cvt_pk_bf16_f32 v81, v82, v83
	v_lshlrev_b32_e32 v82, 16, v94
	v_and_b32_e32 v83, 0xffff0000, v94
	v_pk_mul_f32 v[82:83], v[84:85], v[82:83]
	v_lshlrev_b32_e32 v84, 16, v95
	v_and_b32_e32 v85, 0xffff0000, v95
	v_pk_mul_f32 v[84:85], v[86:87], v[84:85]
	v_cvt_pk_bf16_f32 v82, v82, v83
	v_cvt_pk_bf16_f32 v83, v84, v85
	s_nop 1
	v_mfma_f32_16x16x32_bf16 v[140:143], v[32:35], v[80:83], v[72:75]
	s_waitcnt vmcnt(32)
	v_mfma_f32_16x16x32_bf16 v[136:139], v[36:39], v[80:83], v[76:79]
	s_ashr_i32 s22, s22, 5
	s_ashr_i32 s23, s22, 31
	s_lshl_b64 s[22:23], s[22:23], 10
	v_lshl_add_u64 v[36:37], v[154:155], 0, s[22:23]
	global_load_dwordx4 v[92:95], v[36:37], off
	global_load_dwordx4 v[80:83], v[36:37], off offset:1024
	global_load_dwordx4 v[72:75], v[36:37], off offset:2048
	global_load_dwordx4 v[32:35], v[36:37], off offset:3072
	v_add_co_u32_e32 v36, vcc, s36, v36
	s_nop 1
	v_addc_co_u32_e32 v37, vcc, 0, v37, vcc
	global_load_dwordx4 v[96:99], v[36:37], off
	global_load_dwordx4 v[84:87], v[36:37], off offset:1024
	global_load_dwordx4 v[76:79], v[36:37], off offset:2048
	s_nop 0
	global_load_dwordx4 v[36:39], v[36:37], off offset:3072
	s_barrier
	s_waitcnt vmcnt(39)
	ds_write_b128 v164, v[108:111]
	v_cvt_pk_bf16_f32 v108, v140, v141
	v_cvt_pk_bf16_f32 v109, v142, v143
	v_cvt_pk_bf16_f32 v110, v136, v137
	v_cvt_pk_bf16_f32 v111, v138, v139
	ds_write2_b64 v176, v[108:109], v[110:111] offset0:32 offset1:36
	s_and_saveexec_b64 s[22:23], s[44:45]
	s_cbranch_execz .LBB0_496
	s_waitcnt vmcnt(38)
	v_mul_f32_e64 v110, v173, -v163
	s_waitcnt vmcnt(37)
	v_mul_f32_e64 v109, v175, -v163
	s_and_b64 vcc, exec, s[70:71]
	v_mov_b32_e32 v111, v110
	v_mov_b32_e32 v178, v109
	s_cbranch_vccz .Lsc1_bwd
	v_add_f32_dpp v111, v110, v111 row_shr:1 row_mask:0xf bank_mask:0xf bound_ctrl:0
	v_add_f32_dpp v178, v109, v178 row_shr:1 row_mask:0xf bank_mask:0xf bound_ctrl:0
	v_add_f32_dpp v111, v110, v111 row_shr:2 row_mask:0xf bank_mask:0xf bound_ctrl:0
	v_add_f32_dpp v178, v109, v178 row_shr:2 row_mask:0xf bank_mask:0xf bound_ctrl:0
	v_add_f32_dpp v111, v110, v111 row_shr:3 row_mask:0xf bank_mask:0xf bound_ctrl:0
	v_add_f32_dpp v178, v109, v178 row_shr:3 row_mask:0xf bank_mask:0xf bound_ctrl:0
	s_nop 1
	v_add_f32_dpp v111, v111, v111 row_shr:4 row_mask:0xf bank_mask:0xe
	v_add_f32_dpp v178, v178, v178 row_shr:4 row_mask:0xf bank_mask:0xe
	s_nop 1
	v_add_f32_dpp v111, v111, v111 row_shr:8 row_mask:0xf bank_mask:0xc
	v_add_f32_dpp v178, v178, v178 row_shr:8 row_mask:0xf bank_mask:0xc
	s_nop 1
	v_add_f32_dpp v111, v111, v111 row_bcast:15 row_mask:0xa bank_mask:0xf
	v_add_f32_dpp v178, v178, v178 row_bcast:15 row_mask:0xa bank_mask:0xf
	s_nop 1
	v_add_f32_dpp v111, v111, v111 row_bcast:31 row_mask:0xc bank_mask:0xf
	v_add_f32_dpp v178, v178, v178 row_bcast:31 row_mask:0xc bank_mask:0xf
	s_nop 1
	v_readlane_b32 s24, v111, 63
	s_nop 3
	v_add_f32_e32 v178, s24, v178
	s_nop 1
	v_readlane_b32 s24, v178, 63
	s_nop 3
	v_mov_b32_e32 v108, s24
	s_branch .Lsc1_join
; __device__ __forceinline__ f32x2 scan128(float s0, float s1, int lane, int dir) {
;     if (dir == 0) {
; #pragma unroll
;         for (int o = 1; o < 64; o <<= 1) { const float t0 = __shfl_up(s0, o), t1 = __shfl_up(s1, o); s0 += lane >= o ? t0 : 0.f; s1 += lane >= o ? t1 : 0.f; }
;         s1 += __shfl(s0, 63);
;     } else {
; #pragma unroll
;         for (int o = 1; o < 64; o <<= 1) { const float t0 = __shfl_down(s0, o), t1 = __shfl_down(s1, o); s0 += lane + o < 64 ? t0 : 0.f; s1 += lane + o < 64 ? t1 : 0.f; }
;         s0 += __shfl(s1, 0);
;     }
;     return (f32x2){s0, s1};
; }
; __device__ __forceinline__ void ssd_scan_item(CParams& p, int j2, int b, int dir, int h, int pq, bf16_t* smem) {
;     ...
;             const float total = dir == 0 ? __shfl(sc2.y, 63) : __shfl(sc2.x, 0);
;             if (wave == 0) { seacs[lane] = __expf(sc2.x); sw[lane] = S.dt0 * __expf(total - sc2.x); if (lane == 0) sdec[0] = __expf(total); }
;             else { seacs[64 + lane] = __expf(sc2.y); sw[64 + lane] = S.dt1 * __expf(total - sc2.y); }
.Lsc1_bwd:
	v_add_f32_dpp v111, v110, v111 row_shl:1 row_mask:0xf bank_mask:0xf bound_ctrl:0
	v_add_f32_dpp v178, v109, v178 row_shl:1 row_mask:0xf bank_mask:0xf bound_ctrl:0
	v_add_f32_dpp v111, v110, v111 row_shl:2 row_mask:0xf bank_mask:0xf bound_ctrl:0
	v_add_f32_dpp v178, v109, v178 row_shl:2 row_mask:0xf bank_mask:0xf bound_ctrl:0
	v_add_f32_dpp v111, v110, v111 row_shl:3 row_mask:0xf bank_mask:0xf bound_ctrl:0
	v_add_f32_dpp v178, v109, v178 row_shl:3 row_mask:0xf bank_mask:0xf bound_ctrl:0
	s_nop 1
	v_add_f32_dpp v111, v111, v111 row_shl:4 row_mask:0xf bank_mask:0x7
	v_add_f32_dpp v178, v178, v178 row_shl:4 row_mask:0xf bank_mask:0x7
	s_nop 1
	v_add_f32_dpp v111, v111, v111 row_shl:8 row_mask:0xf bank_mask:0x3
	v_add_f32_dpp v178, v178, v178 row_shl:8 row_mask:0xf bank_mask:0x3
	s_nop 1
	v_readlane_b32 s24, v111, 48
	v_readlane_b32 s25, v178, 48
	s_nop 3
	v_mov_b32_e32 v176, s24
	v_mov_b32_e32 v179, s25
	s_nop 1
	v_add_f32_dpp v111, v176, v111 quad_perm:[0,1,2,3] row_mask:0x4 bank_mask:0xf
	v_add_f32_dpp v178, v179, v178 quad_perm:[0,1,2,3] row_mask:0x4 bank_mask:0xf
	s_nop 1
	v_readlane_b32 s24, v111, 32
	v_readlane_b32 s25, v178, 32
	s_nop 3
	v_mov_b32_e32 v176, s24
	v_mov_b32_e32 v179, s25
	s_nop 1
	v_add_f32_dpp v111, v176, v111 quad_perm:[0,1,2,3] row_mask:0x2 bank_mask:0xf
	v_add_f32_dpp v178, v179, v178 quad_perm:[0,1,2,3] row_mask:0x2 bank_mask:0xf
	s_nop 1
	v_readlane_b32 s24, v111, 16
	v_readlane_b32 s25, v178, 16
	s_nop 3
	v_mov_b32_e32 v176, s24
	v_mov_b32_e32 v179, s25
	s_nop 1
	v_add_f32_dpp v111, v176, v111 quad_perm:[0,1,2,3] row_mask:0x1 bank_mask:0xf
	v_add_f32_dpp v178, v179, v178 quad_perm:[0,1,2,3] row_mask:0x1 bank_mask:0xf
	s_nop 1
	v_readlane_b32 s24, v178, 0
	s_nop 3
	v_add_f32_e32 v111, s24, v111
	s_nop 1
	v_readlane_b32 s24, v111, 0
	s_nop 3
	v_mov_b32_e32 v108, s24
.Lsc1_join:
	s_and_saveexec_b64 s[24:25], s[68:69]
	s_xor_b64 s[24:25], exec, s[24:25]
	s_cbranch_execz .Lsc1_w0
	v_sub_f32_e32 v108, v108, v178
	v_mul_f32_e32 v108, 0x3fb8aa3b, v108
	v_mul_f32_e32 v109, 0x3fb8aa3b, v178
	v_exp_f32_e32 v108, v108
	v_exp_f32_e32 v109, v109
	s_nop 0
	v_mul_f32_e32 v108, v175, v108
	ds_write2st64_b32 v174, v109, v108 offset0:35 offset1:37
.Lsc1_w0:
	s_andn2_saveexec_b64 s[24:25], s[24:25]
	s_cbranch_execz .LBB0_496
	v_sub_f32_e32 v110, v108, v111
	v_mul_f32_e32 v110, 0x3fb8aa3b, v110
	v_mul_f32_e32 v109, 0x3fb8aa3b, v111
	v_exp_f32_e32 v110, v110
	v_exp_f32_e32 v109, v109
	s_nop 0
	v_mul_f32_e32 v110, v173, v110
	ds_write2st64_b32 v174, v109, v110 offset0:34 offset1:36
	s_and_b64 exec, exec, s[58:59]
	s_cbranch_execz .LBB0_496
	v_mul_f32_e32 v108, 0x3fb8aa3b, v108
	v_exp_f32_e32 v108, v108
	ds_write_b32 v165, v108 offset:9728
